# P2 queue: latent attention unit fetches its next item index when its key loop ends (atomic round trip hidden under the last tile + finalize)
# baseline (speedup 1.0000x reference)
_Z11mega_kernel5KArgs:
	s_load_dwordx16 s[4:19], s[0:1], 0x80
	s_add_u32 s30, s0, 0xc0
	s_addc_u32 s31, s1, 0
	s_waitcnt lgkmcnt(0)
	s_add_u32 s44, s18, 0x12e100
	v_writelane_b32 v255, 0, 54
	v_writelane_b32 v254, s4, 0
	s_addc_u32 s45, s19, 0
	s_cmp_eq_u32 s2, 0
	v_writelane_b32 v254, s5, 1
	v_writelane_b32 v254, s6, 2
	v_writelane_b32 v254, s7, 3
	v_writelane_b32 v254, s8, 4
	v_writelane_b32 v254, s9, 5
	v_writelane_b32 v254, s10, 6
	v_writelane_b32 v254, s11, 7
	v_writelane_b32 v254, s12, 8
	v_writelane_b32 v254, s13, 9
	v_writelane_b32 v254, s14, 10
	v_writelane_b32 v254, s15, 11
	v_writelane_b32 v254, s16, 12
	v_writelane_b32 v254, s17, 13
	v_writelane_b32 v254, s18, 14
	v_writelane_b32 v254, s19, 15
	s_cbranch_scc1 .LBB0_2
	v_and_b32_e32 v222, 0x3ff, v0
	s_load_dword s95, s[0:1], 0xc0
	s_cbranch_execz .LBB0_3
	s_branch .LBB0_6

.LBB0_700:
	v_mov_b32_e32 v212, v222
	s_nop 0
	v_cmp_eq_u32_e32 vcc, 0, v212
	s_barrier
	s_and_saveexec_b64 s[2:3], vcc
	s_cbranch_execz .LBB0_704
	s_mov_b64 s[10:11], exec
	v_mbcnt_lo_u32_b32 v1, s10, 0
	v_mbcnt_hi_u32_b32 v1, s11, v1
	v_cmp_eq_u32_e32 vcc, 0, v1
	s_and_saveexec_b64 s[4:5], vcc
	s_cbranch_execz .LBB0_703
	s_bcnt1_i32_b64 s7, s[10:11]
	v_readlane_b32 s10, v255, 54
	s_nop 0
	s_cmp_eq_u32 s10, 0
	s_cbranch_scc1 .Lq_fetch
	s_mov_b32 s10, 0
	s_nop 0
	v_writelane_b32 v255, s10, 54
	s_waitcnt vmcnt(0)
	v_mov_b32_e32 v2, v229
	s_branch .Lq_have
.Lq_fetch:
	v_readlane_b32 s10, v255, 37
	v_mov_b32_e32 v2, s7
	v_readlane_b32 s11, v255, 38
	s_nop 4
	global_atomic_add v2, v211, v2, s[10:11] offset:64 sc0
.Lq_have:
.LBB0_703:
	s_or_b64 exec, exec, s[4:5]
	s_waitcnt vmcnt(0)
	v_readfirstlane_b32 s4, v2
	s_nop 1
	v_add_u32_e32 v1, s4, v1
	ds_write_b32 v214, v1

.LBB0_902:
	s_cmp_lg_u32 s3, 0
	s_cbranch_scc1 .Lqpf_skip
	s_mov_b64 exec, 1
	v_readlane_b32 s4, v255, 37
	v_readlane_b32 s5, v255, 38
	v_mov_b32_e32 v229, 1
	s_mov_b32 s11, 1
	v_writelane_b32 v255, s11, 54
	s_nop 1
	global_atomic_add v229, v211, v229, s[4:5] offset:64 sc0
	s_mov_b64 exec, -1
